# speedup vs baseline: 1.0427x; 1.0079x over previous
; __device__ __forceinline__ int v_st(int k, int c) { const int kk = (k & ~0xC) | ((k & 4) << 1) | ((k & 8) >> 1); return ((kk >> 3) * 4 + (c >> 5)) * 512 + ((kk & 7) * 32 + (c & 31)) * 2; }
; __device__ __forceinline__ void sgu_unit(const Params& p, int l, int chunk, int g, char* lds) {
;     ...
;     __syncthreads();
;     const int sr = tid >> 4, sc = (tid & 15) * 8;
; #pragma unroll
;     for (int st = 0; st < 2; ++st)
; #pragma unroll
;         for (int d2 = 0; d2 < 2; ++d2) { char* T = lds + (st * 2 + d2) * 16384;
;             const bf16x8 v0 = *(const bf16x8*)(rows + (size_t)(st * 64 + sr) * NP + C_AV + g * 256 + d2 * 128 + sc);
;             const bf16x8 v1 = *(const bf16x8*)(rows + (size_t)(st * 64 + 32 + sr) * NP + C_AV + g * 256 + d2 * 128 + sc);
;             *(bf16x8*)(T + v_st(sr, sc)) = v0; *(bf16x8*)(T + v_st(32 + sr, sc)) = v1; }
;     bf16x8 pa[8];
; #pragma unroll
;     for (int kb = 0; kb < 8; ++kb) pa[kb] = *(const bf16x8*)(WSM + (size_t)(tb * 32 + r32) * 128 + kb * 16 + hi * 8);
.LBB0_174:
	v_mov_b32_e32 v16, v159
	s_mov_b32 s8, 24
	s_ashr_i32 s9, s8, 31
	s_ashr_i32 s5, s4, 2
	s_and_b32 s12, s4, 3
	s_lshl_b64 s[8:9], s[8:9], 3
	s_add_u32 s8, s0, s8
	s_addc_u32 s9, s1, s9
	s_load_dwordx2 s[8:9], s[8:9], 0x0
	v_ashrrev_i32_e32 v17, 4, v16
	v_and_b32_e32 v2, 0xfffff0, v17
	v_lshlrev_b32_e32 v3, 1, v17
	v_lshlrev_b32_e32 v0, 3, v16
	v_and_or_b32 v2, v3, 8, v2
	s_mul_i32 s11, s5, 0x410000
	v_and_b32_e32 v4, 0x78, v0
	v_lshrrev_b32_e32 v2, 1, v2
	v_bfe_u32 v0, v0, 5, 2
	s_mul_hi_i32 s10, s5, 0x410000
	s_waitcnt lgkmcnt(0)
	s_add_u32 s11, s8, s11
	v_or_b32_e32 v2, v2, v0
	s_addc_u32 s13, s9, s10
	v_add_u32_e32 v5, 32, v17
	v_lshrrev_b32_e32 v3, 1, v17
	v_lshlrev_b32_e32 v18, 9, v2
	v_and_b32_e32 v2, 3, v17
	s_add_u32 s10, s11, 0xa1a1000
	v_and_or_b32 v19, v3, 4, v2
	v_and_b32_e32 v2, 0xfffff0, v5
	v_lshlrev_b32_e32 v3, 1, v5
	s_addc_u32 s11, s13, 0
	v_and_or_b32 v2, v3, 8, v2
	v_lshrrev_b32_e32 v2, 1, v2
	v_mov_b64_e32 v[10:11], s[10:11]
	v_or_b32_e32 v0, v2, v0
	v_mad_i64_i32 v[2:3], s[16:17], v17, s3, v[10:11]
	s_lshl_b32 s72, s12, 9
	v_lshlrev_b32_e32 v22, 9, v0
	v_lshl_add_u64 v[2:3], v[2:3], 0, s[72:73]
	v_lshlrev_b32_e32 v0, 1, v4
	v_lshl_add_u64 v[12:13], v[2:3], 0, v[0:1]
	v_mad_i64_i32 v[2:3], s[16:17], v5, s3, v[10:11]
	v_lshl_add_u64 v[2:3], v[2:3], 0, s[72:73]
	s_waitcnt vmcnt(0)
	s_barrier
	v_lshl_add_u64 v[14:15], v[2:3], 0, v[0:1]
	global_load_dwordx4 v[24:27], v[12:13], off offset:2048
	global_load_dwordx4 v[28:31], v[14:15], off offset:2048
	global_load_dwordx4 v[32:35], v[12:13], off offset:2304
	global_load_dwordx4 v[36:39], v[14:15], off offset:2304
	v_lshlrev_b32_e32 v20, 4, v16
	v_and_b32_e32 v21, 48, v20
	v_lshl_add_u32 v19, v19, 6, 0
	v_add3_u32 v18, v19, v18, v21
	v_add3_u32 v19, v19, v22, v21
	v_and_b32_e32 v94, 31, v16
	s_lshl_b32 s14, s12, 8
	s_lshl_b32 s12, s12, 15
	v_bfe_u32 v95, v16, 6, 2
	s_add_u32 s12, s8, s12
	v_bfe_u32 v96, v16, 5, 1
	s_addc_u32 s13, s9, 0
	s_cmp_lg_u32 0, -1
	v_add_u32_e32 v2, 64, v17
	v_mad_i64_i32 v[2:3], s[16:17], v2, s3, v[10:11]
	v_lshl_add_u64 v[2:3], v[2:3], 0, s[72:73]
	v_lshl_add_u64 v[12:13], v[2:3], 0, v[0:1]
	v_add_u32_e32 v2, 0x60, v17
	v_mad_i64_i32 v[2:3], s[16:17], v2, s3, v[10:11]
	v_lshl_add_u64 v[2:3], v[2:3], 0, s[72:73]
	v_lshl_add_u64 v[10:11], v[2:3], 0, v[0:1]
	global_load_dwordx4 v[40:43], v[12:13], off offset:2048
	global_load_dwordx4 v[44:47], v[10:11], off offset:2048
	global_load_dwordx4 v[48:51], v[12:13], off offset:2304
	global_load_dwordx4 v[52:55], v[10:11], off offset:2304
	v_lshlrev_b32_e32 v0, 8, v94
	v_lshl_or_b32 v0, v95, 13, v0
	s_waitcnt vmcnt(7)
	ds_write_b128 v18, v[24:27]
	s_waitcnt vmcnt(6)
	ds_write_b128 v19, v[28:31]
	s_waitcnt vmcnt(5)
	ds_write_b128 v18, v[32:35] offset:16384
	s_waitcnt vmcnt(4)
	ds_write_b128 v19, v[36:39] offset:16384
	s_waitcnt vmcnt(3)
	ds_write_b128 v18, v[40:43] offset:32768
	s_waitcnt vmcnt(2)
	ds_write_b128 v19, v[44:47] offset:32768
	s_waitcnt vmcnt(1)
	ds_write_b128 v18, v[48:51] offset:49152
	s_waitcnt vmcnt(0)
	ds_write_b128 v19, v[52:55] offset:49152
	v_lshl_add_u64 v[2:3], s[12:13], 0, v[0:1]
	v_lshlrev_b32_e32 v0, 4, v96
	v_lshl_add_u64 v[2:3], v[2:3], 0, v[0:1]
	s_mov_b64 s[12:13], 0x6000000
	v_lshl_add_u64 v[6:7], v[2:3], 0, s[12:13]
	s_mov_b32 s12, 0x6000000
	v_add_co_u32_e32 v2, vcc, s12, v2
	v_and_b32_e32 v8, 63, v16
	s_nop 0
	v_addc_co_u32_e32 v3, vcc, 0, v3, vcc
	global_load_dwordx4 v[2:5], v[2:3], off
	s_nop 0
	global_load_dwordx4 v[90:93], v[6:7], off offset:32
	global_load_dwordx4 v[86:89], v[6:7], off offset:64
	global_load_dwordx4 v[82:85], v[6:7], off offset:96
	global_load_dwordx4 v[78:81], v[6:7], off offset:128
	global_load_dwordx4 v[74:77], v[6:7], off offset:160
	global_load_dwordx4 v[70:73], v[6:7], off offset:192
	global_load_dwordx4 v[66:69], v[6:7], off offset:224
	v_lshlrev_b32_e32 v6, 3, v8
	v_lshlrev_b32_e32 v9, 1, v16
	v_ashrrev_i32_e32 v0, 8, v16
	v_and_b32_e32 v7, 24, v6
	v_and_b32_e32 v8, 0xc0, v20
	v_and_b32_e32 v9, 32, v9
	s_cselect_b32 s12, 0, 0
	v_or3_b32 v7, v7, v8, v9
	v_and_b32_e32 v6, 0x100, v6
	v_lshl_add_u32 v8, v0, 14, s12
	s_waitcnt lgkmcnt(0)
	s_barrier
; #define SBAR() __builtin_amdgcn_sched_barrier(0)
; __device__ __forceinline__ int v_rd_base(int lane) { return ((lane & 3) << 3) | (((lane >> 2) & 3) << 6) | (((lane >> 4) & 1) << 5) | (((lane >> 5) & 1) << 8); }
; template <int OFF> __device__ __forceinline__ s16x4 tr_read(int vb) { s16x4 r; asm volatile("ds_read_b64_tr_b16 %0, %1 offset:%2" : "=&v"(r) : "v"(vb), "i"(OFF) : "memory"); return r; }
; template <int D0> __device__ __forceinline__ void pv_one(f32x16& od, int vb, bf16x8 pa0, bf16x8 pa1, bf16x8 pa2, bf16x8 pa3) {
;     const s16x4 l0 = tr_read<v_rd_off(D0, 0, 0)>(vb), h0 = tr_read<v_rd_off(D0, 0, 1)>(vb), l1 = tr_read<v_rd_off(D0, 1, 0)>(vb), h1 = tr_read<v_rd_off(D0, 1, 1)>(vb);
;     const s16x4 l2 = tr_read<v_rd_off(D0, 2, 0)>(vb), h2 = tr_read<v_rd_off(D0, 2, 1)>(vb), l3 = tr_read<v_rd_off(D0, 3, 0)>(vb), h3 = tr_read<v_rd_off(D0, 3, 1)>(vb);
;     asm volatile("s_waitcnt lgkmcnt(0)" ::: "memory"); SBAR();
;     ...
;     od = __builtin_amdgcn_mfma_f32_32x32x16_bf16(PK(l0, h0), pa0, od, 0, 0, 0);
;     od = __builtin_amdgcn_mfma_f32_32x32x16_bf16(PK(l1, h1), pa1, od, 0, 0, 0);
;     od = __builtin_amdgcn_mfma_f32_32x32x16_bf16(PK(l2, h2), pa2, od, 0, 0, 0);
;     od = __builtin_amdgcn_mfma_f32_32x32x16_bf16(PK(l3, h3), pa3, od, 0, 0, 0);
;     ...
; }
; __device__ __forceinline__ void pv_d0(f32x16* o, int vb, bf16x8 pa0, bf16x8 pa1, bf16x8 pa2, bf16x8 pa3) {
;     pv_one<0>(o[0], vb, pa0, pa1, pa2, pa3); pv_one<1>(o[1], vb, pa0, pa1, pa2, pa3); pv_one<2>(o[2], vb, pa0, pa1, pa2, pa3); pv_one<3>(o[3], vb, pa0, pa1, pa2, pa3);
; }
; __device__ __forceinline__ void sgu_unit(const Params& p, int l, int chunk, int g, char* lds) {
;     ...
;     f32x16 o[4] = {};
;     const int vb = (int)(uintptr_t)(lds) + v_rd_base(lane);
;     pv_d0(o, vb + (0 * 2 + dh) * 16384, pa[0], pa[1], pa[2], pa[3]);
;     if (tb >= 2) pv_d0(o, vb + (1 * 2 + dh) * 16384, pa[4], pa[5], pa[6], pa[7]);
	v_add3_u32 v97, v8, v6, v7
	ds_read_b64_tr_b16 v[6:7], v97 offset:0
	ds_read_b64_tr_b16 v[8:9], v97 offset:0x800
	ds_read_b64_tr_b16 v[10:11], v97 offset:0x1000
	ds_read_b64_tr_b16 v[12:13], v97 offset:0x1800
	ds_read_b64_tr_b16 v[14:15], v97 offset:0x2000
	ds_read_b64_tr_b16 v[16:17], v97 offset:0x2800
	ds_read_b64_tr_b16 v[18:19], v97 offset:0x3000
	ds_read_b64_tr_b16 v[20:21], v97 offset:0x3800
	s_waitcnt lgkmcnt(0)
	s_waitcnt vmcnt(7)
	v_mfma_f32_32x32x16_bf16 v[50:65], v[6:9], v[2:5], 0
	ds_read_b64_tr_b16 v[6:7], v97 offset:0x200
	ds_read_b64_tr_b16 v[8:9], v97 offset:0xa00
	s_waitcnt vmcnt(6)
	v_mfma_f32_32x32x16_bf16 v[50:65], v[10:13], v[90:93], v[50:65]
	ds_read_b64_tr_b16 v[10:11], v97 offset:0x1200
	ds_read_b64_tr_b16 v[12:13], v97 offset:0x1a00
	s_waitcnt vmcnt(5)
	v_mfma_f32_32x32x16_bf16 v[50:65], v[14:17], v[86:89], v[50:65]
	ds_read_b64_tr_b16 v[14:15], v97 offset:0x2200
	ds_read_b64_tr_b16 v[16:17], v97 offset:0x2a00
	s_waitcnt vmcnt(4)
	v_mfma_f32_32x32x16_bf16 v[50:65], v[18:21], v[82:85], v[50:65]
	ds_read_b64_tr_b16 v[18:19], v97 offset:0x3200
	ds_read_b64_tr_b16 v[20:21], v97 offset:0x3a00
	s_waitcnt lgkmcnt(0)
	v_mfma_f32_32x32x16_bf16 v[34:49], v[6:9], v[2:5], 0
	ds_read_b64_tr_b16 v[6:7], v97 offset:0x400
	ds_read_b64_tr_b16 v[8:9], v97 offset:0xc00
	v_mfma_f32_32x32x16_bf16 v[34:49], v[10:13], v[90:93], v[34:49]
	ds_read_b64_tr_b16 v[10:11], v97 offset:0x1400
	ds_read_b64_tr_b16 v[12:13], v97 offset:0x1c00
	v_mfma_f32_32x32x16_bf16 v[34:49], v[14:17], v[86:89], v[34:49]
	ds_read_b64_tr_b16 v[14:15], v97 offset:0x2400
	ds_read_b64_tr_b16 v[16:17], v97 offset:0x2c00
	ds_read_b64_tr_b16 v[98:99], v97 offset:0x3400
	ds_read_b64_tr_b16 v[100:101], v97 offset:0x3c00
	s_waitcnt lgkmcnt(0)
	v_mfma_f32_32x32x16_bf16 v[34:49], v[18:21], v[82:85], v[34:49]
	v_mfma_f32_32x32x16_bf16 v[18:33], v[6:9], v[2:5], 0
	ds_read_b64_tr_b16 v[6:7], v97 offset:0x600
	ds_read_b64_tr_b16 v[8:9], v97 offset:0xe00
	v_mfma_f32_32x32x16_bf16 v[18:33], v[10:13], v[90:93], v[18:33]
	v_mfma_f32_32x32x16_bf16 v[18:33], v[14:17], v[86:89], v[18:33]
	v_mfma_f32_32x32x16_bf16 v[18:33], v[98:101], v[82:85], v[18:33]
	ds_read_b64_tr_b16 v[98:99], v97 offset:0x1600
	ds_read_b64_tr_b16 v[100:101], v97 offset:0x1e00
	ds_read_b64_tr_b16 v[102:103], v97 offset:0x2600
	ds_read_b64_tr_b16 v[104:105], v97 offset:0x2e00
	ds_read_b64_tr_b16 v[106:107], v97 offset:0x3600
	ds_read_b64_tr_b16 v[108:109], v97 offset:0x3e00
	s_waitcnt lgkmcnt(0)
	v_mfma_f32_32x32x16_bf16 v[2:17], v[6:9], v[2:5], 0
	v_cmp_lt_u32_e32 vcc, 1, v95
	v_mfma_f32_32x32x16_bf16 v[2:17], v[98:101], v[90:93], v[2:17]
	v_mfma_f32_32x32x16_bf16 v[2:17], v[102:105], v[86:89], v[2:17]
	v_mfma_f32_32x32x16_bf16 v[2:17], v[106:109], v[82:85], v[2:17]
	s_and_saveexec_b64 s[12:13], vcc
	s_cbranch_execz .LBB0_173
	v_add_u32_e32 v97, 0x8000, v97
	ds_read_b64_tr_b16 v[82:83], v97 offset:0
	ds_read_b64_tr_b16 v[84:85], v97 offset:0x800
	ds_read_b64_tr_b16 v[86:87], v97 offset:0x1000
	ds_read_b64_tr_b16 v[88:89], v97 offset:0x1800
	ds_read_b64_tr_b16 v[90:91], v97 offset:0x2000
	ds_read_b64_tr_b16 v[92:93], v97 offset:0x2800
	ds_read_b64_tr_b16 v[98:99], v97 offset:0x3000
	ds_read_b64_tr_b16 v[100:101], v97 offset:0x3800
	s_waitcnt lgkmcnt(0)
	s_waitcnt vmcnt(3)
	v_mfma_f32_32x32x16_bf16 v[50:65], v[82:85], v[78:81], v[50:65]
	ds_read_b64_tr_b16 v[82:83], v97 offset:0x200
	ds_read_b64_tr_b16 v[84:85], v97 offset:0xa00
	s_waitcnt vmcnt(2)
	v_mfma_f32_32x32x16_bf16 v[50:65], v[86:89], v[74:77], v[50:65]
	ds_read_b64_tr_b16 v[86:87], v97 offset:0x1200
	ds_read_b64_tr_b16 v[88:89], v97 offset:0x1a00
	s_waitcnt vmcnt(1)
	v_mfma_f32_32x32x16_bf16 v[50:65], v[90:93], v[70:73], v[50:65]
	ds_read_b64_tr_b16 v[90:91], v97 offset:0x2200
	ds_read_b64_tr_b16 v[92:93], v97 offset:0x2a00
	s_waitcnt vmcnt(0)
	v_mfma_f32_32x32x16_bf16 v[50:65], v[98:101], v[66:69], v[50:65]
	ds_read_b64_tr_b16 v[98:99], v97 offset:0x3200
	ds_read_b64_tr_b16 v[100:101], v97 offset:0x3a00
	s_waitcnt lgkmcnt(0)
	v_mfma_f32_32x32x16_bf16 v[34:49], v[82:85], v[78:81], v[34:49]
	ds_read_b64_tr_b16 v[82:83], v97 offset:0x400
	ds_read_b64_tr_b16 v[84:85], v97 offset:0xc00
	v_mfma_f32_32x32x16_bf16 v[34:49], v[86:89], v[74:77], v[34:49]
	ds_read_b64_tr_b16 v[86:87], v97 offset:0x1400
	ds_read_b64_tr_b16 v[88:89], v97 offset:0x1c00
	v_mfma_f32_32x32x16_bf16 v[34:49], v[90:93], v[70:73], v[34:49]
	ds_read_b64_tr_b16 v[90:91], v97 offset:0x2400
	ds_read_b64_tr_b16 v[92:93], v97 offset:0x2c00
	v_mfma_f32_32x32x16_bf16 v[34:49], v[98:101], v[66:69], v[34:49]
	ds_read_b64_tr_b16 v[98:99], v97 offset:0x3400
	ds_read_b64_tr_b16 v[100:101], v97 offset:0x3c00
	s_waitcnt lgkmcnt(0)
	v_mfma_f32_32x32x16_bf16 v[18:33], v[82:85], v[78:81], v[18:33]
	ds_read_b64_tr_b16 v[82:83], v97 offset:0x600
	ds_read_b64_tr_b16 v[84:85], v97 offset:0xe00
	v_mfma_f32_32x32x16_bf16 v[18:33], v[86:89], v[74:77], v[18:33]
	ds_read_b64_tr_b16 v[86:87], v97 offset:0x1600
	ds_read_b64_tr_b16 v[88:89], v97 offset:0x1e00
	v_mfma_f32_32x32x16_bf16 v[18:33], v[90:93], v[70:73], v[18:33]
	ds_read_b64_tr_b16 v[90:91], v97 offset:0x2600
	ds_read_b64_tr_b16 v[92:93], v97 offset:0x2e00
	v_mfma_f32_32x32x16_bf16 v[18:33], v[98:101], v[66:69], v[18:33]
	ds_read_b64_tr_b16 v[98:99], v97 offset:0x3600
	ds_read_b64_tr_b16 v[100:101], v97 offset:0x3e00
	s_waitcnt lgkmcnt(0)
	v_mfma_f32_32x32x16_bf16 v[2:17], v[82:85], v[78:81], v[2:17]
	v_mfma_f32_32x32x16_bf16 v[2:17], v[86:89], v[74:77], v[2:17]
	v_mfma_f32_32x32x16_bf16 v[2:17], v[90:93], v[70:73], v[2:17]
	v_mfma_f32_32x32x16_bf16 v[2:17], v[98:101], v[66:69], v[2:17]
	s_branch .LBB0_173

; __device__ __forceinline__ int opaque_tid() { int t = threadIdx.x; asm volatile("" : "+v"(t)); return t; }
; __device__ __forceinline__ float bf2f(bf16_t b) { return __uint_as_float(((unsigned)b) << 16); }
; __device__ __forceinline__ bf16_t f2bf(float f) { return (bf16_t)(cvt_pk(f, 0.f) & 0xffffu); }
; __device__ __forceinline__ float siluf(float x) { return x * __builtin_amdgcn_rcpf(1.f + __expf(-x)); }
; __device__ __forceinline__ void sgu_sample(const Params& p, int l) {
;     ...
;     for (int i = blockIdx.x * NTH + opaque_tid(); i < TS * 1024; i += gridDim.x * NTH) {
;         const int col = i & 1023, rr = i >> 10, b = rr >> 4, t = rr & 15, g = col >> 8;
;         float acc = bias[g * 128 + t];
;         for (int s = 0; s <= t; ++s) acc += bf2f(WSM[(size_t)g * 16384 + t * 128 + s]) * bf2f(proj[(size_t)(TP + b * 16 + s) * NP + C_AV + col]);
;         bf16_t* rp = proj + (size_t)(TP + rr) * NP;
;         ((bf16_t*)(ws + WS_YA))[(size_t)(TP + rr) * 1024 + col] = f2bf(bf2f(rp[C_AU + col]) * acc * siluf(bf2f(rp[C_AZ + col])));
;     }
.LBB0_185:
	v_ashrrev_i32_e32 v10, 10, v8
	v_and_b32_e32 v0, 15, v10
	v_lshlrev_b32_e32 v2, 1, v8
	v_lshlrev_b32_e32 v3, 2, v0
	s_movk_i32 s4, 0x600
	v_and_or_b32 v2, v2, s4, v3
	global_load_dword v2, v2, s[10:11]
	v_and_b32_e32 v6, -16, v10
	v_and_b32_e32 v4, 0x3ff, v9
	v_mul_hi_i32_i24_e32 v5, 0x8200, v6
	v_mul_i32_i24_e32 v6, 0x8200, v6
	v_add_u32_e32 v11, 1, v0
	v_lshl_or_b32 v4, v4, 1, v6
	v_lshlrev_b32_e32 v6, 7, v9
	v_lshlrev_b32_e32 v0, 8, v0
	s_mov_b32 s4, 0x18000
	v_and_or_b32 v0, v6, s4, v0
	v_and_b32_e32 v3, 0x3ff, v8
	v_lshl_add_u64 v[4:5], s[14:15], 0, v[4:5]
	v_lshl_add_u64 v[6:7], s[16:17], 0, v[0:1]
	s_mov_b64 s[20:21], 0
	s_mov_b64 s[4:5], 0x8200
	global_load_ushort v16, v[6:7], off
	global_load_ushort v32, v[4:5], off
	v_lshl_add_u64 v[4:5], v[4:5], 0, s[4:5]
	global_load_ushort v17, v[6:7], off offset:2
	global_load_ushort v33, v[4:5], off
	v_lshl_add_u64 v[4:5], v[4:5], 0, s[4:5]
	global_load_ushort v18, v[6:7], off offset:4
	global_load_ushort v34, v[4:5], off
	v_lshl_add_u64 v[4:5], v[4:5], 0, s[4:5]
	global_load_ushort v19, v[6:7], off offset:6
	global_load_ushort v35, v[4:5], off
	v_lshl_add_u64 v[4:5], v[4:5], 0, s[4:5]
	global_load_ushort v20, v[6:7], off offset:8
	global_load_ushort v36, v[4:5], off
	v_lshl_add_u64 v[4:5], v[4:5], 0, s[4:5]
	global_load_ushort v21, v[6:7], off offset:10
	global_load_ushort v37, v[4:5], off
	v_lshl_add_u64 v[4:5], v[4:5], 0, s[4:5]
	global_load_ushort v22, v[6:7], off offset:12
	global_load_ushort v38, v[4:5], off
	v_lshl_add_u64 v[4:5], v[4:5], 0, s[4:5]
	global_load_ushort v23, v[6:7], off offset:14
	global_load_ushort v39, v[4:5], off
	v_lshl_add_u64 v[4:5], v[4:5], 0, s[4:5]
	global_load_ushort v24, v[6:7], off offset:16
	global_load_ushort v40, v[4:5], off
	v_lshl_add_u64 v[4:5], v[4:5], 0, s[4:5]
	global_load_ushort v25, v[6:7], off offset:18
	global_load_ushort v41, v[4:5], off
	v_lshl_add_u64 v[4:5], v[4:5], 0, s[4:5]
	global_load_ushort v26, v[6:7], off offset:20
	global_load_ushort v42, v[4:5], off
	v_lshl_add_u64 v[4:5], v[4:5], 0, s[4:5]
	global_load_ushort v27, v[6:7], off offset:22
	global_load_ushort v43, v[4:5], off
	v_lshl_add_u64 v[4:5], v[4:5], 0, s[4:5]
	global_load_ushort v28, v[6:7], off offset:24
	global_load_ushort v44, v[4:5], off
	v_lshl_add_u64 v[4:5], v[4:5], 0, s[4:5]
	global_load_ushort v29, v[6:7], off offset:26
	global_load_ushort v45, v[4:5], off
	v_lshl_add_u64 v[4:5], v[4:5], 0, s[4:5]
	global_load_ushort v30, v[6:7], off offset:28
	global_load_ushort v46, v[4:5], off
	v_lshl_add_u64 v[4:5], v[4:5], 0, s[4:5]
	global_load_ushort v31, v[6:7], off offset:30
	global_load_ushort v47, v[4:5], off
	s_waitcnt vmcnt(30)
	v_lshlrev_b32_e32 v16, 16, v16
	v_lshlrev_b32_e32 v32, 16, v32
	v_fmac_f32_e32 v2, v32, v16
	s_waitcnt vmcnt(28)
	v_lshlrev_b32_e32 v17, 16, v17
	v_lshlrev_b32_e32 v33, 16, v33
	v_fmac_f32_e32 v2, v33, v17
	s_waitcnt vmcnt(26)
	v_lshlrev_b32_e32 v18, 16, v18
	v_lshlrev_b32_e32 v34, 16, v34
	v_fmac_f32_e32 v2, v34, v18
	s_waitcnt vmcnt(24)
	v_lshlrev_b32_e32 v19, 16, v19
	v_lshlrev_b32_e32 v35, 16, v35
	v_fmac_f32_e32 v2, v35, v19
	s_waitcnt vmcnt(22)
	v_lshlrev_b32_e32 v20, 16, v20
	v_lshlrev_b32_e32 v36, 16, v36
	v_fmac_f32_e32 v2, v36, v20
	s_waitcnt vmcnt(20)
	v_lshlrev_b32_e32 v21, 16, v21
	v_lshlrev_b32_e32 v37, 16, v37
	v_fmac_f32_e32 v2, v37, v21
	s_waitcnt vmcnt(18)
	v_lshlrev_b32_e32 v22, 16, v22
	v_lshlrev_b32_e32 v38, 16, v38
	v_fmac_f32_e32 v2, v38, v22
	s_waitcnt vmcnt(16)
	v_lshlrev_b32_e32 v23, 16, v23
	v_lshlrev_b32_e32 v39, 16, v39
	v_fmac_f32_e32 v2, v39, v23
	s_waitcnt vmcnt(14)
	v_lshlrev_b32_e32 v24, 16, v24
	v_lshlrev_b32_e32 v40, 16, v40
	v_fmac_f32_e32 v2, v40, v24
	s_waitcnt vmcnt(12)
	v_lshlrev_b32_e32 v25, 16, v25
	v_lshlrev_b32_e32 v41, 16, v41
	v_fmac_f32_e32 v2, v41, v25
	s_waitcnt vmcnt(10)
	v_lshlrev_b32_e32 v26, 16, v26
	v_lshlrev_b32_e32 v42, 16, v42
	v_fmac_f32_e32 v2, v42, v26
	s_waitcnt vmcnt(8)
	v_lshlrev_b32_e32 v27, 16, v27
	v_lshlrev_b32_e32 v43, 16, v43
	v_fmac_f32_e32 v2, v43, v27
	s_waitcnt vmcnt(6)
	v_lshlrev_b32_e32 v28, 16, v28
	v_lshlrev_b32_e32 v44, 16, v44
	v_fmac_f32_e32 v2, v44, v28
	s_waitcnt vmcnt(4)
	v_lshlrev_b32_e32 v29, 16, v29
	v_lshlrev_b32_e32 v45, 16, v45
	v_fmac_f32_e32 v2, v45, v29
	s_waitcnt vmcnt(2)
	v_lshlrev_b32_e32 v30, 16, v30
	v_lshlrev_b32_e32 v46, 16, v46
	v_fmac_f32_e32 v2, v46, v30
	s_waitcnt vmcnt(0)
	v_lshlrev_b32_e32 v31, 16, v31
	v_lshlrev_b32_e32 v47, 16, v47
	v_fmac_f32_e32 v2, v47, v31
	s_or_b64 exec, exec, s[20:21]
	v_add_u32_e32 v4, 0x4000, v10
	v_mul_hi_i32_i24_e32 v7, 0x8200, v4
	v_mul_i32_i24_e32 v6, 0x8200, v4
	v_lshl_add_u64 v[6:7], s[8:9], 0, v[6:7]
	v_lshlrev_b32_e32 v0, 1, v3
	v_lshl_add_u64 v[6:7], v[6:7], 0, v[0:1]
	v_add_co_u32_e32 v10, vcc, 0x1000, v6
	v_ashrrev_i32_e32 v5, 31, v4
	s_nop 0
	v_addc_co_u32_e32 v11, vcc, 0, v7, vcc
	global_load_ushort v3, v[10:11], off
	s_nop 0
	global_load_ushort v6, v[6:7], off
	v_add_u32_e32 v8, s75, v8
	s_mov_b32 s4, 0x1ffff
	v_lshlrev_b64 v[4:5], 11, v[4:5]
	v_cmp_lt_i32_e32 vcc, s4, v8
	v_lshl_add_u64 v[4:5], s[12:13], 0, v[4:5]
	s_or_b64 s[18:19], vcc, s[18:19]
	v_lshl_add_u64 v[4:5], v[4:5], 0, v[0:1]
	v_subrev_u16_e32 v9, s75, v9
	s_waitcnt vmcnt(1)
	v_lshlrev_b32_e32 v7, 16, v3
	v_mul_f32_e32 v3, 0xbfb8aa3b, v7
	v_exp_f32_e32 v3, v3
	s_waitcnt vmcnt(0)
	v_lshlrev_b32_e32 v6, 16, v6
	v_add_f32_e32 v3, 1.0, v3
	v_rcp_f32_e32 v3, v3
	s_nop 0
	v_pk_mul_f32 v[2:3], v[2:3], v[6:7]
	s_nop 0
	v_mul_f32_e32 v0, v2, v3
	v_cvt_pk_bf16_f32 v0, v0, v1
	global_store_short v[4:5], v0, off
	s_andn2_b64 exec, exec, s[18:19]
	s_cbranch_execnz .LBB0_185
